# P8/P11 row reductions via DPP + permlane swaps instead of 6 ds_bpermute round trips each (on top of v23)
# baseline (speedup 1.0000x reference)
; __device__ __forceinline__ unsigned pk2(float lo, float hi) { const f32x2_h v = {lo, hi}; return __builtin_bit_cast(unsigned, __builtin_convertvector(v, bf16x2_h)); }
; __global__ void __launch_bounds__(512, 2) fwd_megakernel(Params p) {
;     ...
;             const u32x2* r8 = (const u32x2*)(MB + (size_t)m * DM) + lane; const f32x4* xr = (const f32x4*)xrow_ptr(p, m) + lane; f32x4 v[8]; float s = 0.f;
; #pragma unroll
;             for (int j = 0; j < 8; ++j) { const u32x2 w = r8[64 * j]; v[j] = (f32x4){__uint_as_float(w.x << 16), __uint_as_float(w.x & 0xffff0000u), __uint_as_float(w.y << 16), __uint_as_float(w.y & 0xffff0000u)};
;                 s += (v[j].x * v[j].x + v[j].y * v[j].y) + (v[j].z * v[j].z + v[j].w * v[j].w); }
;             const float rm = 1.f / sqrtf(wave_sum(s) * (1.f / DM) + RMS_EPS); float s1 = 0.f;
;             u32x2* h8 = (u32x2*)(Hb + (size_t)m * DM) + lane;
; #pragma unroll
;             for (int j = 0; j < 8; ++j) { const f32x4 gg = *(const f32x4*)(gpo + 4 * lane + 256 * j); v[j] = xr[64 * j] + v[j] * rm * gg;
;                 s1 += (v[j].x * v[j].x + v[j].y * v[j].y) + (v[j].z * v[j].z + v[j].w * v[j].w);
;                 u32x2 o; o.x = pk2(v[j].x, v[j].y); o.y = pk2(v[j].z, v[j].w); h8[64 * j] = o; }
.Lp8_nopfA:
	v_pk_mul_f32 v[146:147], v[0:1], v[0:1]
	v_pk_mul_f32 v[148:149], v[2:3], v[2:3]
	v_pk_fma_f32 v[146:147], v[4:5], v[4:5], v[146:147]
	v_pk_fma_f32 v[148:149], v[6:7], v[6:7], v[148:149]
	v_pk_fma_f32 v[146:147], v[8:9], v[8:9], v[146:147]
	v_pk_fma_f32 v[148:149], v[10:11], v[10:11], v[148:149]
	v_pk_fma_f32 v[146:147], v[12:13], v[12:13], v[146:147]
	v_pk_fma_f32 v[148:149], v[14:15], v[14:15], v[148:149]
	v_pk_fma_f32 v[146:147], v[16:17], v[16:17], v[146:147]
	v_pk_fma_f32 v[148:149], v[18:19], v[18:19], v[148:149]
	v_pk_fma_f32 v[146:147], v[20:21], v[20:21], v[146:147]
	v_pk_fma_f32 v[148:149], v[22:23], v[22:23], v[148:149]
	v_pk_fma_f32 v[146:147], v[24:25], v[24:25], v[146:147]
	v_pk_fma_f32 v[148:149], v[26:27], v[26:27], v[148:149]
	v_pk_fma_f32 v[146:147], v[28:29], v[28:29], v[146:147]
	v_pk_fma_f32 v[148:149], v[30:31], v[30:31], v[148:149]
	s_nop 0
	v_pk_add_f32 v[146:147], v[146:147], v[148:149]
	s_nop 0
	v_add_f32_e32 v150, v146, v147
	s_nop 1
	v_add_f32_dpp v150, v150, v150 quad_perm:[1,0,3,2] row_mask:0xf bank_mask:0xf
	s_nop 1
	v_add_f32_dpp v150, v150, v150 quad_perm:[2,3,0,1] row_mask:0xf bank_mask:0xf
	s_nop 1
	v_add_f32_dpp v150, v150, v150 row_half_mirror row_mask:0xf bank_mask:0xf
	s_nop 1
	v_add_f32_dpp v150, v150, v150 row_mirror row_mask:0xf bank_mask:0xf
	v_mov_b32_e32 v151, v150
	s_nop 1
	v_permlane16_swap_b32_e32 v150, v151
	v_add_f32_e32 v150, v150, v151
	v_mov_b32_e32 v151, v150
	s_nop 1
	v_permlane32_swap_b32_e32 v150, v151
	v_add_f32_e32 v150, v150, v151
	v_fmamk_f32 v150, v150, 0x3a000000, v33
	v_mul_f32_e32 v156, 0x4f800000, v150
	v_cmp_gt_f32_e32 vcc, s10, v150
	s_nop 1
	v_cndmask_b32_e32 v150, v150, v156, vcc
	v_sqrt_f32_e32 v156, v150
	s_nop 0
	v_add_u32_e32 v152, -1, v156
	v_add_u32_e32 v153, 1, v156
	v_fma_f32 v154, -v152, v156, v150
	v_fma_f32 v155, -v153, v156, v150
	v_cmp_ge_f32_e64 s[6:7], 0, v154
	s_nop 1
	v_cndmask_b32_e64 v156, v156, v152, s[6:7]
	v_cmp_lt_f32_e64 s[6:7], 0, v155
	s_nop 1
	v_cndmask_b32_e64 v156, v156, v153, s[6:7]
	v_mul_f32_e32 v152, 0x37800000, v156
	v_cndmask_b32_e32 v156, v156, v152, vcc
	v_cmp_class_f32_e32 vcc, v150, v34
	s_nop 1
	v_cndmask_b32_e32 v150, v156, v150, vcc
	v_div_scale_f32 v156, s[6:7], v150, v150, 1.0
	v_rcp_f32_e32 v153, v156
	v_div_scale_f32 v152, vcc, 1.0, v150, 1.0
	v_fma_f32 v154, -v156, v153, 1.0
	v_fmac_f32_e32 v153, v154, v153
	v_mul_f32_e32 v154, v152, v153
	v_fma_f32 v155, -v156, v154, v152
	v_fmac_f32_e32 v154, v155, v153
	v_fma_f32 v156, -v156, v154, v152
	v_div_fmas_f32 v156, v156, v153, v154
	v_div_fixup_f32 v156, v156, v150, 1.0
	v_pk_mul_f32 v[204:205], v[156:157], v[0:1] op_sel_hi:[0,1]
	v_pk_mul_f32 v[206:207], v[156:157], v[2:3] op_sel_hi:[0,1]
	v_pk_fma_f32 v[72:73], v[208:209], v[204:205], v[72:73]
	v_pk_fma_f32 v[74:75], v[210:211], v[206:207], v[74:75]
	v_pk_mul_f32 v[204:205], v[156:157], v[4:5] op_sel_hi:[0,1]
	v_pk_mul_f32 v[206:207], v[156:157], v[6:7] op_sel_hi:[0,1]
	v_pk_fma_f32 v[76:77], v[212:213], v[204:205], v[76:77]
	v_pk_fma_f32 v[78:79], v[214:215], v[206:207], v[78:79]
	v_pk_mul_f32 v[204:205], v[156:157], v[8:9] op_sel_hi:[0,1]
	v_pk_mul_f32 v[206:207], v[156:157], v[10:11] op_sel_hi:[0,1]
	v_pk_fma_f32 v[80:81], v[216:217], v[204:205], v[80:81]
	v_pk_fma_f32 v[82:83], v[218:219], v[206:207], v[82:83]
	v_pk_mul_f32 v[204:205], v[156:157], v[12:13] op_sel_hi:[0,1]
	v_pk_mul_f32 v[206:207], v[156:157], v[14:15] op_sel_hi:[0,1]
	v_pk_fma_f32 v[84:85], v[220:221], v[204:205], v[84:85]
	v_pk_fma_f32 v[86:87], v[222:223], v[206:207], v[86:87]
	v_pk_mul_f32 v[204:205], v[156:157], v[16:17] op_sel_hi:[0,1]
	v_pk_mul_f32 v[206:207], v[156:157], v[18:19] op_sel_hi:[0,1]
	v_pk_fma_f32 v[88:89], v[224:225], v[204:205], v[88:89]
	v_pk_fma_f32 v[90:91], v[226:227], v[206:207], v[90:91]
	v_pk_mul_f32 v[204:205], v[156:157], v[20:21] op_sel_hi:[0,1]
	v_pk_mul_f32 v[206:207], v[156:157], v[22:23] op_sel_hi:[0,1]
	v_pk_fma_f32 v[92:93], v[228:229], v[204:205], v[92:93]
	v_pk_fma_f32 v[94:95], v[230:231], v[206:207], v[94:95]
	v_pk_mul_f32 v[204:205], v[156:157], v[24:25] op_sel_hi:[0,1]
	v_pk_mul_f32 v[206:207], v[156:157], v[26:27] op_sel_hi:[0,1]
	v_pk_fma_f32 v[96:97], v[232:233], v[204:205], v[96:97]
	v_pk_fma_f32 v[98:99], v[234:235], v[206:207], v[98:99]
	v_pk_mul_f32 v[204:205], v[156:157], v[28:29] op_sel_hi:[0,1]
	v_pk_mul_f32 v[206:207], v[156:157], v[30:31] op_sel_hi:[0,1]
	v_pk_fma_f32 v[100:101], v[236:237], v[204:205], v[100:101]
	v_pk_fma_f32 v[102:103], v[238:239], v[206:207], v[102:103]
	v_pk_mul_f32 v[146:147], v[72:73], v[72:73]
	v_pk_mul_f32 v[148:149], v[74:75], v[74:75]
	v_pk_fma_f32 v[146:147], v[76:77], v[76:77], v[146:147]
	v_pk_fma_f32 v[148:149], v[78:79], v[78:79], v[148:149]
	v_pk_fma_f32 v[146:147], v[80:81], v[80:81], v[146:147]
	v_pk_fma_f32 v[148:149], v[82:83], v[82:83], v[148:149]
	v_pk_fma_f32 v[146:147], v[84:85], v[84:85], v[146:147]
	v_pk_fma_f32 v[148:149], v[86:87], v[86:87], v[148:149]
	v_pk_fma_f32 v[146:147], v[88:89], v[88:89], v[146:147]
	v_pk_fma_f32 v[148:149], v[90:91], v[90:91], v[148:149]
	v_pk_fma_f32 v[146:147], v[92:93], v[92:93], v[146:147]
	v_pk_fma_f32 v[148:149], v[94:95], v[94:95], v[148:149]
	v_pk_fma_f32 v[146:147], v[96:97], v[96:97], v[146:147]
	v_pk_fma_f32 v[148:149], v[98:99], v[98:99], v[148:149]
	v_pk_fma_f32 v[146:147], v[100:101], v[100:101], v[146:147]
	v_pk_fma_f32 v[148:149], v[102:103], v[102:103], v[148:149]
	v_cvt_pk_bf16_f32 v40, v72, v73
	v_cvt_pk_bf16_f32 v41, v74, v75
	global_store_dwordx2 v162, v[40:41], s[24:25]
	v_cvt_pk_bf16_f32 v42, v76, v77
	v_cvt_pk_bf16_f32 v43, v78, v79
	global_store_dwordx2 v162, v[42:43], s[24:25] offset:512
; __device__ __forceinline__ unsigned pk2(float lo, float hi) { const f32x2_h v = {lo, hi}; return __builtin_bit_cast(unsigned, __builtin_convertvector(v, bf16x2_h)); }
; __global__ void __launch_bounds__(512, 2) fwd_megakernel(Params p) {
;     ...
;         for (int m = gw; m < MROWS; m += NGW) {
;             const u32x2* r8 = (const u32x2*)(MB + (size_t)m * DM) + lane; const f32x4* xr = (const f32x4*)xrow_ptr(p, m) + lane; f32x4 v[8]; float s = 0.f;
; #pragma unroll
;             for (int j = 0; j < 8; ++j) { const u32x2 w = r8[64 * j]; v[j] = (f32x4){__uint_as_float(w.x << 16), __uint_as_float(w.x & 0xffff0000u), __uint_as_float(w.y << 16), __uint_as_float(w.y & 0xffff0000u)};
;                 s += (v[j].x * v[j].x + v[j].y * v[j].y) + (v[j].z * v[j].z + v[j].w * v[j].w); }
;             const float rm = 1.f / sqrtf(wave_sum(s) * (1.f / DM) + RMS_EPS); float s1 = 0.f;
;             u32x2* h8 = (u32x2*)(Hb + (size_t)m * DM) + lane;
; #pragma unroll
;             for (int j = 0; j < 8; ++j) { const f32x4 gg = *(const f32x4*)(gpo + 4 * lane + 256 * j); v[j] = xr[64 * j] + v[j] * rm * gg;
;                 s1 += (v[j].x * v[j].x + v[j].y * v[j].y) + (v[j].z * v[j].z + v[j].w * v[j].w);
;                 u32x2 o; o.x = pk2(v[j].x, v[j].y); o.y = pk2(v[j].z, v[j].w); h8[64 * j] = o; }
;             s1 = wave_sum(s1);
;             if (lane == 0) rsq_x[m] = s1;
	v_cvt_pk_bf16_f32 v44, v80, v81
	v_cvt_pk_bf16_f32 v45, v82, v83
	global_store_dwordx2 v162, v[44:45], s[24:25] offset:1024
	v_cvt_pk_bf16_f32 v46, v84, v85
	v_cvt_pk_bf16_f32 v47, v86, v87
	global_store_dwordx2 v162, v[46:47], s[24:25] offset:1536
	v_cvt_pk_bf16_f32 v48, v88, v89
	v_cvt_pk_bf16_f32 v49, v90, v91
	global_store_dwordx2 v162, v[48:49], s[24:25] offset:2048
	v_cvt_pk_bf16_f32 v50, v92, v93
	v_cvt_pk_bf16_f32 v51, v94, v95
	global_store_dwordx2 v162, v[50:51], s[24:25] offset:2560
	v_cvt_pk_bf16_f32 v52, v96, v97
	v_cvt_pk_bf16_f32 v53, v98, v99
	global_store_dwordx2 v162, v[52:53], s[24:25] offset:3072
	v_cvt_pk_bf16_f32 v54, v100, v101
	v_cvt_pk_bf16_f32 v55, v102, v103
	global_store_dwordx2 v162, v[54:55], s[24:25] offset:3584
	v_pk_add_f32 v[146:147], v[146:147], v[148:149]
	s_nop 0
	v_add_f32_e32 v150, v146, v147
	s_nop 1
	v_add_f32_dpp v150, v150, v150 quad_perm:[1,0,3,2] row_mask:0xf bank_mask:0xf
	s_nop 1
	v_add_f32_dpp v150, v150, v150 quad_perm:[2,3,0,1] row_mask:0xf bank_mask:0xf
	s_nop 1
	v_add_f32_dpp v150, v150, v150 row_half_mirror row_mask:0xf bank_mask:0xf
	s_nop 1
	v_add_f32_dpp v150, v150, v150 row_mirror row_mask:0xf bank_mask:0xf
	v_mov_b32_e32 v151, v150
	s_nop 1
	v_permlane16_swap_b32_e32 v150, v151
	v_add_f32_e32 v150, v150, v151
	v_mov_b32_e32 v151, v150
	s_nop 1
	v_permlane32_swap_b32_e32 v150, v151
	v_add_f32_e32 v150, v150, v151
	s_and_saveexec_b64 s[6:7], s[4:5]
	global_store_dword v35, v150, s[26:27]
	s_mov_b64 exec, s[6:7]
	s_cmpk_gt_i32 s14, 0x5fff
	s_cbranch_scc1 .LBB0_835
	s_waitcnt vmcnt(9)
	v_lshlrev_b32_e32 v0, 16, v56
	v_and_b32_e32 v1, 0xffff0000, v56
	v_lshlrev_b32_e32 v2, 16, v57
	v_and_b32_e32 v3, 0xffff0000, v57
	v_lshlrev_b32_e32 v4, 16, v58
	v_and_b32_e32 v5, 0xffff0000, v58
	v_lshlrev_b32_e32 v6, 16, v59
	v_and_b32_e32 v7, 0xffff0000, v59
	v_lshlrev_b32_e32 v8, 16, v60
	v_and_b32_e32 v9, 0xffff0000, v60
	v_lshlrev_b32_e32 v10, 16, v61
	v_and_b32_e32 v11, 0xffff0000, v61
	v_lshlrev_b32_e32 v12, 16, v62
	v_and_b32_e32 v13, 0xffff0000, v62
	v_lshlrev_b32_e32 v14, 16, v63
	v_and_b32_e32 v15, 0xffff0000, v63
	v_lshlrev_b32_e32 v16, 16, v64
	v_and_b32_e32 v17, 0xffff0000, v64
	v_lshlrev_b32_e32 v18, 16, v65
	v_and_b32_e32 v19, 0xffff0000, v65
	v_lshlrev_b32_e32 v20, 16, v66
	v_and_b32_e32 v21, 0xffff0000, v66
	v_lshlrev_b32_e32 v22, 16, v67
	v_and_b32_e32 v23, 0xffff0000, v67
	v_lshlrev_b32_e32 v24, 16, v68
	v_and_b32_e32 v25, 0xffff0000, v68
	v_lshlrev_b32_e32 v26, 16, v69
	v_and_b32_e32 v27, 0xffff0000, v69
	v_lshlrev_b32_e32 v28, 16, v70
	v_and_b32_e32 v29, 0xffff0000, v70
	v_lshlrev_b32_e32 v30, 16, v71
	v_and_b32_e32 v31, 0xffff0000, v71
	s_ashr_i32 s15, s14, 31
	s_lshl_b64 s[8:9], s[14:15], 12
	s_add_u32 s24, s42, s8
	s_addc_u32 s25, s43, s9
	s_lshl_b64 s[8:9], s[14:15], 2
	s_add_u32 s26, s44, s8
	s_addc_u32 s27, s45, s9
	s_add_i32 s14, s14, s62
	s_cmpk_gt_i32 s14, 0x5fff
	s_cbranch_scc1 .Lp8_nopfB
	s_ashr_i32 s7, s14, 31
	s_mov_b32 s6, s14
	s_lshl_b64 s[8:9], s[6:7], 12
	s_add_u32 s16, s40, s8
	s_addc_u32 s17, s41, s9
	s_add_i32 s8, s14, 0xffffe000
	s_cmpk_lt_i32 s14, 0x2000
	s_cselect_b32 s8, s14, s8
	s_cselect_b32 s18, s36, s38
	s_cselect_b32 s19, s37, s39
	s_ashr_i32 s9, s8, 31
	s_lshl_b64 s[8:9], s[8:9], 13
	s_add_u32 s18, s18, s8
	s_addc_u32 s19, s19, s9
	s_add_u32 s20, s18, 0x1000
	s_addc_u32 s21, s19, 0
	global_load_dwordx2 v[40:41], v162, s[16:17]
	global_load_dwordx2 v[42:43], v162, s[16:17] offset:512
	global_load_dwordx2 v[44:45], v162, s[16:17] offset:1024
	global_load_dwordx2 v[46:47], v162, s[16:17] offset:1536
	global_load_dwordx2 v[48:49], v162, s[16:17] offset:2048
	global_load_dwordx2 v[50:51], v162, s[16:17] offset:2560
	global_load_dwordx2 v[52:53], v162, s[16:17] offset:3072
	global_load_dwordx2 v[54:55], v162, s[16:17] offset:3584
	global_load_dwordx4 v[72:75], v160, s[18:19]
	global_load_dwordx4 v[76:79], v160, s[18:19] offset:1024
	global_load_dwordx4 v[80:83], v160, s[18:19] offset:2048
	global_load_dwordx4 v[84:87], v160, s[18:19] offset:3072
	global_load_dwordx4 v[88:91], v160, s[20:21]
	global_load_dwordx4 v[92:95], v160, s[20:21] offset:1024
	global_load_dwordx4 v[96:99], v160, s[20:21] offset:2048
	global_load_dwordx4 v[100:103], v160, s[20:21] offset:3072
.Lp8_nopfB:
	v_pk_mul_f32 v[146:147], v[0:1], v[0:1]
	v_pk_mul_f32 v[148:149], v[2:3], v[2:3]
	v_pk_fma_f32 v[146:147], v[4:5], v[4:5], v[146:147]
	v_pk_fma_f32 v[148:149], v[6:7], v[6:7], v[148:149]
	v_pk_fma_f32 v[146:147], v[8:9], v[8:9], v[146:147]
	v_pk_fma_f32 v[148:149], v[10:11], v[10:11], v[148:149]
	v_pk_fma_f32 v[146:147], v[12:13], v[12:13], v[146:147]
	v_pk_fma_f32 v[148:149], v[14:15], v[14:15], v[148:149]
	v_pk_fma_f32 v[146:147], v[16:17], v[16:17], v[146:147]
	v_pk_fma_f32 v[148:149], v[18:19], v[18:19], v[148:149]
	v_pk_fma_f32 v[146:147], v[20:21], v[20:21], v[146:147]
	v_pk_fma_f32 v[148:149], v[22:23], v[22:23], v[148:149]
	v_pk_fma_f32 v[146:147], v[24:25], v[24:25], v[146:147]
	v_pk_fma_f32 v[148:149], v[26:27], v[26:27], v[148:149]
	v_pk_fma_f32 v[146:147], v[28:29], v[28:29], v[146:147]
	v_pk_fma_f32 v[148:149], v[30:31], v[30:31], v[148:149]
	s_nop 0
	v_pk_add_f32 v[146:147], v[146:147], v[148:149]
	s_nop 0
	v_add_f32_e32 v150, v146, v147
	s_nop 1
	v_add_f32_dpp v150, v150, v150 quad_perm:[1,0,3,2] row_mask:0xf bank_mask:0xf
	s_nop 1
	v_add_f32_dpp v150, v150, v150 quad_perm:[2,3,0,1] row_mask:0xf bank_mask:0xf
	s_nop 1
	v_add_f32_dpp v150, v150, v150 row_half_mirror row_mask:0xf bank_mask:0xf
	s_nop 1
	v_add_f32_dpp v150, v150, v150 row_mirror row_mask:0xf bank_mask:0xf
	v_mov_b32_e32 v151, v150
	s_nop 1
	v_permlane16_swap_b32_e32 v150, v151
	v_add_f32_e32 v150, v150, v151
; __device__ __forceinline__ unsigned pk2(float lo, float hi) { const f32x2_h v = {lo, hi}; return __builtin_bit_cast(unsigned, __builtin_convertvector(v, bf16x2_h)); }
; __global__ void __launch_bounds__(512, 2) fwd_megakernel(Params p) {
;     ...
;             const u32x2* r8 = (const u32x2*)(MB + (size_t)m * DM) + lane; const f32x4* xr = (const f32x4*)xrow_ptr(p, m) + lane; f32x4 v[8]; float s = 0.f;
; #pragma unroll
;             for (int j = 0; j < 8; ++j) { const u32x2 w = r8[64 * j]; v[j] = (f32x4){__uint_as_float(w.x << 16), __uint_as_float(w.x & 0xffff0000u), __uint_as_float(w.y << 16), __uint_as_float(w.y & 0xffff0000u)};
;                 s += (v[j].x * v[j].x + v[j].y * v[j].y) + (v[j].z * v[j].z + v[j].w * v[j].w); }
;             const float rm = 1.f / sqrtf(wave_sum(s) * (1.f / DM) + RMS_EPS); float s1 = 0.f;
;             u32x2* h8 = (u32x2*)(Hb + (size_t)m * DM) + lane;
; #pragma unroll
;             for (int j = 0; j < 8; ++j) { const f32x4 gg = *(const f32x4*)(gpo + 4 * lane + 256 * j); v[j] = xr[64 * j] + v[j] * rm * gg;
;                 s1 += (v[j].x * v[j].x + v[j].y * v[j].y) + (v[j].z * v[j].z + v[j].w * v[j].w);
;                 u32x2 o; o.x = pk2(v[j].x, v[j].y); o.y = pk2(v[j].z, v[j].w); h8[64 * j] = o; }
;             s1 = wave_sum(s1);
;             if (lane == 0) rsq_x[m] = s1;
	v_mov_b32_e32 v151, v150
	s_nop 1
	v_permlane32_swap_b32_e32 v150, v151
	v_add_f32_e32 v150, v150, v151
	v_fmamk_f32 v150, v150, 0x3a000000, v33
	v_mul_f32_e32 v156, 0x4f800000, v150
	v_cmp_gt_f32_e32 vcc, s10, v150
	s_nop 1
	v_cndmask_b32_e32 v150, v150, v156, vcc
	v_sqrt_f32_e32 v156, v150
	s_nop 0
	v_add_u32_e32 v152, -1, v156
	v_add_u32_e32 v153, 1, v156
	v_fma_f32 v154, -v152, v156, v150
	v_fma_f32 v155, -v153, v156, v150
	v_cmp_ge_f32_e64 s[6:7], 0, v154
	s_nop 1
	v_cndmask_b32_e64 v156, v156, v152, s[6:7]
	v_cmp_lt_f32_e64 s[6:7], 0, v155
	s_nop 1
	v_cndmask_b32_e64 v156, v156, v153, s[6:7]
	v_mul_f32_e32 v152, 0x37800000, v156
	v_cndmask_b32_e32 v156, v156, v152, vcc
	v_cmp_class_f32_e32 vcc, v150, v34
	s_nop 1
	v_cndmask_b32_e32 v150, v156, v150, vcc
	v_div_scale_f32 v156, s[6:7], v150, v150, 1.0
	v_rcp_f32_e32 v153, v156
	v_div_scale_f32 v152, vcc, 1.0, v150, 1.0
	v_fma_f32 v154, -v156, v153, 1.0
	v_fmac_f32_e32 v153, v154, v153
	v_mul_f32_e32 v154, v152, v153
	v_fma_f32 v155, -v156, v154, v152
	v_fmac_f32_e32 v154, v155, v153
	v_fma_f32 v156, -v156, v154, v152
	v_div_fmas_f32 v156, v156, v153, v154
	v_div_fixup_f32 v156, v156, v150, 1.0
	v_pk_mul_f32 v[204:205], v[156:157], v[0:1] op_sel_hi:[0,1]
	v_pk_mul_f32 v[206:207], v[156:157], v[2:3] op_sel_hi:[0,1]
	v_pk_fma_f32 v[172:173], v[208:209], v[204:205], v[172:173]
	v_pk_fma_f32 v[174:175], v[210:211], v[206:207], v[174:175]
	v_pk_mul_f32 v[204:205], v[156:157], v[4:5] op_sel_hi:[0,1]
	v_pk_mul_f32 v[206:207], v[156:157], v[6:7] op_sel_hi:[0,1]
	v_pk_fma_f32 v[176:177], v[212:213], v[204:205], v[176:177]
	v_pk_fma_f32 v[178:179], v[214:215], v[206:207], v[178:179]
	v_pk_mul_f32 v[204:205], v[156:157], v[8:9] op_sel_hi:[0,1]
	v_pk_mul_f32 v[206:207], v[156:157], v[10:11] op_sel_hi:[0,1]
	v_pk_fma_f32 v[180:181], v[216:217], v[204:205], v[180:181]
	v_pk_fma_f32 v[182:183], v[218:219], v[206:207], v[182:183]
	v_pk_mul_f32 v[204:205], v[156:157], v[12:13] op_sel_hi:[0,1]
	v_pk_mul_f32 v[206:207], v[156:157], v[14:15] op_sel_hi:[0,1]
	v_pk_fma_f32 v[184:185], v[220:221], v[204:205], v[184:185]
	v_pk_fma_f32 v[186:187], v[222:223], v[206:207], v[186:187]
	v_pk_mul_f32 v[204:205], v[156:157], v[16:17] op_sel_hi:[0,1]
	v_pk_mul_f32 v[206:207], v[156:157], v[18:19] op_sel_hi:[0,1]
	v_pk_fma_f32 v[188:189], v[224:225], v[204:205], v[188:189]
	v_pk_fma_f32 v[190:191], v[226:227], v[206:207], v[190:191]
	v_pk_mul_f32 v[204:205], v[156:157], v[20:21] op_sel_hi:[0,1]
	v_pk_mul_f32 v[206:207], v[156:157], v[22:23] op_sel_hi:[0,1]
	v_pk_fma_f32 v[192:193], v[228:229], v[204:205], v[192:193]
	v_pk_fma_f32 v[194:195], v[230:231], v[206:207], v[194:195]
	v_pk_mul_f32 v[204:205], v[156:157], v[24:25] op_sel_hi:[0,1]
	v_pk_mul_f32 v[206:207], v[156:157], v[26:27] op_sel_hi:[0,1]
	v_pk_fma_f32 v[196:197], v[232:233], v[204:205], v[196:197]
	v_pk_fma_f32 v[198:199], v[234:235], v[206:207], v[198:199]
	v_pk_mul_f32 v[204:205], v[156:157], v[28:29] op_sel_hi:[0,1]
	v_pk_mul_f32 v[206:207], v[156:157], v[30:31] op_sel_hi:[0,1]
	v_pk_fma_f32 v[200:201], v[236:237], v[204:205], v[200:201]
	v_pk_fma_f32 v[202:203], v[238:239], v[206:207], v[202:203]
	v_pk_mul_f32 v[146:147], v[172:173], v[172:173]
	v_pk_mul_f32 v[148:149], v[174:175], v[174:175]
	v_pk_fma_f32 v[146:147], v[176:177], v[176:177], v[146:147]
	v_pk_fma_f32 v[148:149], v[178:179], v[178:179], v[148:149]
	v_pk_fma_f32 v[146:147], v[180:181], v[180:181], v[146:147]
	v_pk_fma_f32 v[148:149], v[182:183], v[182:183], v[148:149]
	v_pk_fma_f32 v[146:147], v[184:185], v[184:185], v[146:147]
	v_pk_fma_f32 v[148:149], v[186:187], v[186:187], v[148:149]
	v_pk_fma_f32 v[146:147], v[188:189], v[188:189], v[146:147]
	v_pk_fma_f32 v[148:149], v[190:191], v[190:191], v[148:149]
	v_pk_fma_f32 v[146:147], v[192:193], v[192:193], v[146:147]
	v_pk_fma_f32 v[148:149], v[194:195], v[194:195], v[148:149]
	v_pk_fma_f32 v[146:147], v[196:197], v[196:197], v[146:147]
	v_pk_fma_f32 v[148:149], v[198:199], v[198:199], v[148:149]
	v_pk_fma_f32 v[146:147], v[200:201], v[200:201], v[146:147]
	v_pk_fma_f32 v[148:149], v[202:203], v[202:203], v[148:149]
	v_cvt_pk_bf16_f32 v56, v172, v173
	v_cvt_pk_bf16_f32 v57, v174, v175
	global_store_dwordx2 v162, v[56:57], s[24:25]
	v_cvt_pk_bf16_f32 v58, v176, v177
	v_cvt_pk_bf16_f32 v59, v178, v179
	global_store_dwordx2 v162, v[58:59], s[24:25] offset:512
	v_cvt_pk_bf16_f32 v60, v180, v181
	v_cvt_pk_bf16_f32 v61, v182, v183
	global_store_dwordx2 v162, v[60:61], s[24:25] offset:1024
	v_cvt_pk_bf16_f32 v62, v184, v185
	v_cvt_pk_bf16_f32 v63, v186, v187
	global_store_dwordx2 v162, v[62:63], s[24:25] offset:1536
	v_cvt_pk_bf16_f32 v64, v188, v189
	v_cvt_pk_bf16_f32 v65, v190, v191
	global_store_dwordx2 v162, v[64:65], s[24:25] offset:2048
	v_cvt_pk_bf16_f32 v66, v192, v193
	v_cvt_pk_bf16_f32 v67, v194, v195
	global_store_dwordx2 v162, v[66:67], s[24:25] offset:2560
	v_cvt_pk_bf16_f32 v68, v196, v197
	v_cvt_pk_bf16_f32 v69, v198, v199
	global_store_dwordx2 v162, v[68:69], s[24:25] offset:3072
	v_cvt_pk_bf16_f32 v70, v200, v201
	v_cvt_pk_bf16_f32 v71, v202, v203
	global_store_dwordx2 v162, v[70:71], s[24:25] offset:3584
	v_pk_add_f32 v[146:147], v[146:147], v[148:149]
	s_nop 0
	v_add_f32_e32 v150, v146, v147
	s_nop 1
	v_add_f32_dpp v150, v150, v150 quad_perm:[1,0,3,2] row_mask:0xf bank_mask:0xf
	s_nop 1
	v_add_f32_dpp v150, v150, v150 quad_perm:[2,3,0,1] row_mask:0xf bank_mask:0xf
	s_nop 1
	v_add_f32_dpp v150, v150, v150 row_half_mirror row_mask:0xf bank_mask:0xf
	s_nop 1
	v_add_f32_dpp v150, v150, v150 row_mirror row_mask:0xf bank_mask:0xf
	v_mov_b32_e32 v151, v150
	s_nop 1
	v_permlane16_swap_b32_e32 v150, v151
	v_add_f32_e32 v150, v150, v151
	v_mov_b32_e32 v151, v150
	s_nop 1
	v_permlane32_swap_b32_e32 v150, v151
	v_add_f32_e32 v150, v150, v151
	s_and_saveexec_b64 s[6:7], s[4:5]
	global_store_dword v35, v150, s[26:27]
	s_mov_b64 exec, s[6:7]
	s_cmpk_gt_i32 s14, 0x5fff
	s_cbranch_scc0 .Lp8_topA

; __global__ void __launch_bounds__(512, 2) fwd_megakernel(Params p) {
;     ...
;         for (int m = gw; m < MROWS; m += NGW) {
;             const u32x2* r8 = (const u32x2*)((const bf16_t*)p.out + (size_t)m * 2 * DM) + lane; const u32x2* x8 = (const u32x2*)(Hb + (size_t)m * DM) + lane; f32x4 v[8]; u32x2 xb[8]; float s = 0.f;
; #pragma unroll
;             for (int j = 0; j < 8; ++j) { const u32x2 w = r8[64 * j]; xb[j] = x8[64 * j]; v[j] = (f32x4){__uint_as_float(w.x << 16), __uint_as_float(w.x & 0xffff0000u), __uint_as_float(w.y << 16), __uint_as_float(w.y & 0xffff0000u)};
;                 s += (v[j].x * v[j].x + v[j].y * v[j].y) + (v[j].z * v[j].z + v[j].w * v[j].w); }
;             const float rf = 1.f / sqrtf(wave_sum(s) * (1.f / DM) + RMS_EPS);
;             f32x4* orow = (f32x4*)(p.out + (size_t)m * DM) + lane;
; #pragma unroll
;             for (int j = 0; j < 8; ++j) { const f32x4 gg = *(const f32x4*)(gpf + 4 * lane + 256 * j);
;                 const f32x4 x1 = (f32x4){__uint_as_float(xb[j].x << 16), __uint_as_float(xb[j].x & 0xffff0000u), __uint_as_float(xb[j].y << 16), __uint_as_float(xb[j].y & 0xffff0000u)};
;                 orow[64 * j] = x1 + v[j] * rf * gg; }
.Lp11_nopf:
	v_pk_mul_f32 v[10:11], v[172:173], v[172:173]
	v_pk_mul_f32 v[12:13], v[174:175], v[174:175]
	v_pk_fma_f32 v[10:11], v[176:177], v[176:177], v[10:11]
	v_pk_fma_f32 v[12:13], v[178:179], v[178:179], v[12:13]
	v_pk_fma_f32 v[10:11], v[180:181], v[180:181], v[10:11]
	v_pk_fma_f32 v[12:13], v[182:183], v[182:183], v[12:13]
	v_pk_fma_f32 v[10:11], v[184:185], v[184:185], v[10:11]
	v_pk_fma_f32 v[12:13], v[186:187], v[186:187], v[12:13]
	v_pk_fma_f32 v[10:11], v[188:189], v[188:189], v[10:11]
	v_pk_fma_f32 v[12:13], v[190:191], v[190:191], v[12:13]
	v_pk_fma_f32 v[10:11], v[192:193], v[192:193], v[10:11]
	v_pk_fma_f32 v[12:13], v[194:195], v[194:195], v[12:13]
	v_pk_fma_f32 v[10:11], v[196:197], v[196:197], v[10:11]
	v_pk_fma_f32 v[12:13], v[198:199], v[198:199], v[12:13]
	v_pk_fma_f32 v[10:11], v[200:201], v[200:201], v[10:11]
	v_pk_fma_f32 v[12:13], v[202:203], v[202:203], v[12:13]
	s_nop 0
	v_pk_add_f32 v[10:11], v[10:11], v[12:13]
	s_nop 0
	v_add_f32_e32 v12, v10, v11
	s_nop 1
	v_add_f32_dpp v12, v12, v12 quad_perm:[1,0,3,2] row_mask:0xf bank_mask:0xf
	s_nop 1
	v_add_f32_dpp v12, v12, v12 quad_perm:[2,3,0,1] row_mask:0xf bank_mask:0xf
	s_nop 1
	v_add_f32_dpp v12, v12, v12 row_half_mirror row_mask:0xf bank_mask:0xf
	s_nop 1
	v_add_f32_dpp v12, v12, v12 row_mirror row_mask:0xf bank_mask:0xf
	v_mov_b32_e32 v16, v12
	s_nop 1
	v_permlane16_swap_b32_e32 v12, v16
	v_add_f32_e32 v12, v12, v16
	v_mov_b32_e32 v16, v12
	s_nop 1
	v_permlane32_swap_b32_e32 v12, v16
	v_add_f32_e32 v12, v12, v16
	v_fmamk_f32 v12, v12, 0x3a000000, v33
	v_mul_f32_e32 v16, 0x4f800000, v12
	v_cmp_gt_f32_e32 vcc, s10, v12
	s_nop 1
	v_cndmask_b32_e32 v12, v12, v16, vcc
	v_sqrt_f32_e32 v16, v12
	s_nop 0
	v_add_u32_e32 v14, -1, v16
	v_add_u32_e32 v15, 1, v16
	v_fma_f32 v17, -v14, v16, v12
	v_fma_f32 v18, -v15, v16, v12
	v_cmp_ge_f32_e64 s[0:1], 0, v17
	s_nop 1
	v_cndmask_b32_e64 v16, v16, v14, s[0:1]
	v_cmp_lt_f32_e64 s[0:1], 0, v18
	s_nop 1
	v_cndmask_b32_e64 v16, v16, v15, s[0:1]
	v_mul_f32_e32 v14, 0x37800000, v16
	v_cndmask_b32_e32 v16, v16, v14, vcc
	v_cmp_class_f32_e32 vcc, v12, v34
	s_nop 1
	v_cndmask_b32_e32 v12, v16, v12, vcc
	v_div_scale_f32 v16, s[0:1], v12, v12, 1.0
	v_rcp_f32_e32 v15, v16
	v_div_scale_f32 v14, vcc, 1.0, v12, 1.0
	v_fma_f32 v17, -v16, v15, 1.0
	v_fmac_f32_e32 v15, v17, v15
	v_mul_f32_e32 v17, v14, v15
	v_fma_f32 v18, -v16, v17, v14
	v_fmac_f32_e32 v17, v18, v15
	v_fma_f32 v16, -v16, v17, v14
	v_div_fmas_f32 v16, v16, v15, v17
	v_div_fixup_f32 v16, v16, v12, 1.0
	v_pk_mul_f32 v[20:21], v[16:17], v[172:173] op_sel_hi:[0,1]
	v_pk_mul_f32 v[22:23], v[16:17], v[174:175] op_sel_hi:[0,1]
	v_pk_fma_f32 v[72:73], v[208:209], v[20:21], v[72:73]
	v_pk_fma_f32 v[74:75], v[210:211], v[22:23], v[74:75]
	global_store_dwordx4 v160, v[72:75], s[6:7]
	v_pk_mul_f32 v[20:21], v[16:17], v[176:177] op_sel_hi:[0,1]
	v_pk_mul_f32 v[22:23], v[16:17], v[178:179] op_sel_hi:[0,1]
	v_pk_fma_f32 v[76:77], v[212:213], v[20:21], v[76:77]
	v_pk_fma_f32 v[78:79], v[214:215], v[22:23], v[78:79]
	global_store_dwordx4 v160, v[76:79], s[6:7] offset:1024
	v_pk_mul_f32 v[20:21], v[16:17], v[180:181] op_sel_hi:[0,1]
	v_pk_mul_f32 v[22:23], v[16:17], v[182:183] op_sel_hi:[0,1]
	v_pk_fma_f32 v[80:81], v[216:217], v[20:21], v[80:81]
	v_pk_fma_f32 v[82:83], v[218:219], v[22:23], v[82:83]
	global_store_dwordx4 v160, v[80:83], s[6:7] offset:2048
	v_pk_mul_f32 v[20:21], v[16:17], v[184:185] op_sel_hi:[0,1]
	v_pk_mul_f32 v[22:23], v[16:17], v[186:187] op_sel_hi:[0,1]
	v_pk_fma_f32 v[84:85], v[220:221], v[20:21], v[84:85]
	v_pk_fma_f32 v[86:87], v[222:223], v[22:23], v[86:87]
	global_store_dwordx4 v160, v[84:87], s[6:7] offset:3072
	v_pk_mul_f32 v[20:21], v[16:17], v[188:189] op_sel_hi:[0,1]
	v_pk_mul_f32 v[22:23], v[16:17], v[190:191] op_sel_hi:[0,1]
	v_pk_fma_f32 v[88:89], v[224:225], v[20:21], v[88:89]
	v_pk_fma_f32 v[90:91], v[226:227], v[22:23], v[90:91]
	global_store_dwordx4 v160, v[88:91], s[12:13]
	v_pk_mul_f32 v[20:21], v[16:17], v[192:193] op_sel_hi:[0,1]
	v_pk_mul_f32 v[22:23], v[16:17], v[194:195] op_sel_hi:[0,1]
	v_pk_fma_f32 v[92:93], v[228:229], v[20:21], v[92:93]
	v_pk_fma_f32 v[94:95], v[230:231], v[22:23], v[94:95]
	global_store_dwordx4 v160, v[92:95], s[12:13] offset:1024
	v_pk_mul_f32 v[20:21], v[16:17], v[196:197] op_sel_hi:[0,1]
	v_pk_mul_f32 v[22:23], v[16:17], v[198:199] op_sel_hi:[0,1]
	v_pk_fma_f32 v[96:97], v[232:233], v[20:21], v[96:97]
	v_pk_fma_f32 v[98:99], v[234:235], v[22:23], v[98:99]
	global_store_dwordx4 v160, v[96:99], s[12:13] offset:2048
	v_pk_mul_f32 v[20:21], v[16:17], v[200:201] op_sel_hi:[0,1]
	v_pk_mul_f32 v[22:23], v[16:17], v[202:203] op_sel_hi:[0,1]
	v_pk_fma_f32 v[100:101], v[236:237], v[20:21], v[100:101]
	v_pk_fma_f32 v[102:103], v[238:239], v[22:23], v[102:103]
	global_store_dwordx4 v160, v[100:103], s[12:13] offset:3072
	s_mov_b64 s[6:7], s[16:17]
	s_add_u32 s12, s16, 0x1000
	s_addc_u32 s13, s17, 0
	s_cmpk_gt_i32 s60, 0x5fff
	s_cbranch_scc0 .Lp11_top
